# phase E rstd-table build: all statistic loads issued together with scalar unit-order math; plus prologue-load hoist, aligned loops, HID sc1, phase-B rewrites
# baseline (speedup 1.0000x reference)
.LBB0_473:
	v_readlane_b32 s0, v244, 1
	s_add_u32 s0, s92, s0
	v_readlane_b32 s1, v245, 62
	v_readlane_b32 s6, v245, 33
	s_addc_u32 s1, s93, s1
	v_readlane_b32 s7, v245, 34
	s_add_u32 s0, s0, 0x1d8c0000
	s_addc_u32 s1, s1, 0
	v_cndmask_b32_e64 v0, 0, 1, s[6:7]
	v_cmp_ne_u32_e64 s[52:53], 1, v0
	s_andn2_b64 vcc, exec, s[6:7]
	s_mov_b32 s50, 0
	s_cbranch_vccnz .LBB0_479
	v_mov_b32_e32 v4, v173
	v_readlane_b32 s6, v245, 51
	v_lshlrev_b32_sdwa v0, v207, v4 dst_sel:DWORD dst_unused:UNUSED_PAD src0_sel:DWORD src1_sel:BYTE_0
	v_ashrrev_i32_e32 v6, 8, v4
	s_waitcnt lgkmcnt(0)
	v_lshl_add_u64 v[2:3], s[0:1], 0, v[0:1]
	v_lshlrev_b32_sdwa v0, v208, v4 dst_sel:DWORD dst_unused:UNUSED_PAD src0_sel:DWORD src1_sel:BYTE_0
	v_lshl_or_b32 v0, v6, 10, v0
	v_add_u32_e32 v0, s6, v0
	v_readlane_b32 s6, v247, 0
	v_readlane_b32 s7, v247, 1
	s_nop 1
	v_mov_b64_e32 v[4:5], s[6:7]
	v_mad_i64_i32 v[4:5], s[6:7], s66, v6, v[4:5]
	s_mov_b64 s[6:7], 0
	s_nop 1
	v_readfirstlane_b32 s14, v4
	s_lshl_b32 s15, s66, 1
	s_mov_b32 s23, 0
	s_mov_b32 s21, 0
	s_cmpk_lt_u32 s14, 0xb00
	s_cbranch_scc0 .Letab_issued
	s_and_b32 s18, s14, 7
	s_lshr_b32 s19, s14, 3
	s_mulk_i32 s18, 0x160
	s_add_i32 s18, s18, s19
	s_mul_hi_u32 s19, s18, 0x2e8ba2e9
	s_lshr_b32 s19, s19, 4
	s_mul_i32 s20, s19, 0x58
	s_sub_i32 s20, s18, s20
	s_and_b32 s20, s20, 3
	s_lshl_b32 s19, s19, 2
	s_add_i32 s19, s19, s20
	s_lshl_b32 s22, s19, 11
	v_lshl_add_u64 v[24:25], v[2:3], 0, s[22:23]
	global_load_dwordx2 v[12:13], v[24:25], off
	s_add_i32 s14, s14, s15
	s_add_i32 s21, s21, 1
	s_cmpk_lt_u32 s14, 0xb00
	s_cbranch_scc0 .Letab_issued
	s_and_b32 s18, s14, 7
	s_lshr_b32 s19, s14, 3
	s_mulk_i32 s18, 0x160
	s_add_i32 s18, s18, s19
	s_mul_hi_u32 s19, s18, 0x2e8ba2e9
	s_lshr_b32 s19, s19, 4
	s_mul_i32 s20, s19, 0x58
	s_sub_i32 s20, s18, s20
	s_and_b32 s20, s20, 3
	s_lshl_b32 s19, s19, 2
	s_add_i32 s19, s19, s20
	s_lshl_b32 s22, s19, 11
	v_lshl_add_u64 v[24:25], v[2:3], 0, s[22:23]
	global_load_dwordx2 v[14:15], v[24:25], off
	s_add_i32 s14, s14, s15
	s_add_i32 s21, s21, 1
	s_cmpk_lt_u32 s14, 0xb00
	s_cbranch_scc0 .Letab_issued
	s_and_b32 s18, s14, 7
	s_lshr_b32 s19, s14, 3
	s_mulk_i32 s18, 0x160
	s_add_i32 s18, s18, s19
	s_mul_hi_u32 s19, s18, 0x2e8ba2e9
	s_lshr_b32 s19, s19, 4
	s_mul_i32 s20, s19, 0x58
	s_sub_i32 s20, s18, s20
	s_and_b32 s20, s20, 3
	s_lshl_b32 s19, s19, 2
	s_add_i32 s19, s19, s20
	s_lshl_b32 s22, s19, 11
	v_lshl_add_u64 v[24:25], v[2:3], 0, s[22:23]
	global_load_dwordx2 v[16:17], v[24:25], off
	s_add_i32 s14, s14, s15
	s_add_i32 s21, s21, 1
	s_cmpk_lt_u32 s14, 0xb00
	s_cbranch_scc0 .Letab_issued
	s_and_b32 s18, s14, 7
	s_lshr_b32 s19, s14, 3
	s_mulk_i32 s18, 0x160
	s_add_i32 s18, s18, s19
	s_mul_hi_u32 s19, s18, 0x2e8ba2e9
	s_lshr_b32 s19, s19, 4
	s_mul_i32 s20, s19, 0x58
	s_sub_i32 s20, s18, s20
	s_and_b32 s20, s20, 3
	s_lshl_b32 s19, s19, 2
	s_add_i32 s19, s19, s20
	s_lshl_b32 s22, s19, 11
	v_lshl_add_u64 v[24:25], v[2:3], 0, s[22:23]
	global_load_dwordx2 v[18:19], v[24:25], off
	s_add_i32 s14, s14, s15
	s_add_i32 s21, s21, 1
	s_cmpk_lt_u32 s14, 0xb00
	s_cbranch_scc0 .Letab_issued
	s_and_b32 s18, s14, 7
	s_lshr_b32 s19, s14, 3
	s_mulk_i32 s18, 0x160
	s_add_i32 s18, s18, s19
	s_mul_hi_u32 s19, s18, 0x2e8ba2e9
	s_lshr_b32 s19, s19, 4
	s_mul_i32 s20, s19, 0x58
	s_sub_i32 s20, s18, s20
	s_and_b32 s20, s20, 3
	s_lshl_b32 s19, s19, 2
	s_add_i32 s19, s19, s20
	s_lshl_b32 s22, s19, 11
	v_lshl_add_u64 v[24:25], v[2:3], 0, s[22:23]
	global_load_dwordx2 v[20:21], v[24:25], off
	s_add_i32 s14, s14, s15
	s_add_i32 s21, s21, 1
	s_cmpk_lt_u32 s14, 0xb00
	s_cbranch_scc0 .Letab_issued
	s_and_b32 s18, s14, 7
	s_lshr_b32 s19, s14, 3
	s_mulk_i32 s18, 0x160
	s_add_i32 s18, s18, s19
	s_mul_hi_u32 s19, s18, 0x2e8ba2e9
	s_lshr_b32 s19, s19, 4
	s_mul_i32 s20, s19, 0x58
	s_sub_i32 s20, s18, s20
	s_and_b32 s20, s20, 3
	s_lshl_b32 s19, s19, 2
	s_add_i32 s19, s19, s20
	s_lshl_b32 s22, s19, 11
	v_lshl_add_u64 v[24:25], v[2:3], 0, s[22:23]
	global_load_dwordx2 v[22:23], v[24:25], off
	s_add_i32 s14, s14, s15
	s_add_i32 s21, s21, 1
.Letab_issued:
	s_waitcnt vmcnt(0)
	s_cmp_gt_u32 s21, 0
	s_cbranch_scc0 .Letab_done
	v_ffbh_u32_e32 v26, v13
	v_min_u32_e32 v26, 32, v26
	v_lshlrev_b64 v[12:13], v26, v[12:13]
	v_min_u32_e32 v12, 1, v12
	v_or_b32_e32 v12, v13, v12
	v_cvt_f32_u32_e32 v12, v12
	v_sub_u32_e32 v13, 32, v26
	v_ldexp_f32 v12, v12, v13
	v_mul_f32_e32 v12, 0x31800000, v12
	v_fmamk_f32 v12, v12, 0x3a800000, v172
	v_mul_f32_e32 v13, 0x4b800000, v12
	v_cmp_gt_f32_e32 vcc, s16, v12
	s_nop 1
	v_cndmask_b32_e32 v12, v12, v13, vcc
	v_rsq_f32_e32 v12, v12
	s_nop 0
	v_mul_f32_e32 v13, 0x45800000, v12
	v_cndmask_b32_e32 v12, v12, v13, vcc
	ds_write_b32 v0, v12
	s_cmp_gt_u32 s21, 1
	s_cbranch_scc0 .Letab_done
	v_ffbh_u32_e32 v26, v15
	v_min_u32_e32 v26, 32, v26
	v_lshlrev_b64 v[14:15], v26, v[14:15]
	v_min_u32_e32 v14, 1, v14
	v_or_b32_e32 v14, v15, v14
	v_cvt_f32_u32_e32 v14, v14
	v_sub_u32_e32 v15, 32, v26
	v_ldexp_f32 v14, v14, v15
	v_mul_f32_e32 v14, 0x31800000, v14
	v_fmamk_f32 v14, v14, 0x3a800000, v172
	v_mul_f32_e32 v15, 0x4b800000, v14
	v_cmp_gt_f32_e32 vcc, s16, v14
	s_nop 1
	v_cndmask_b32_e32 v14, v14, v15, vcc
	v_rsq_f32_e32 v14, v14
	s_nop 0
	v_mul_f32_e32 v15, 0x45800000, v14
	v_cndmask_b32_e32 v14, v14, v15, vcc
	ds_write_b32 v0, v14 offset:2048
	s_cmp_gt_u32 s21, 2
	s_cbranch_scc0 .Letab_done
	v_ffbh_u32_e32 v26, v17
	v_min_u32_e32 v26, 32, v26
	v_lshlrev_b64 v[16:17], v26, v[16:17]
	v_min_u32_e32 v16, 1, v16
	v_or_b32_e32 v16, v17, v16
	v_cvt_f32_u32_e32 v16, v16
	v_sub_u32_e32 v17, 32, v26
	v_ldexp_f32 v16, v16, v17
	v_mul_f32_e32 v16, 0x31800000, v16
	v_fmamk_f32 v16, v16, 0x3a800000, v172
	v_mul_f32_e32 v17, 0x4b800000, v16
	v_cmp_gt_f32_e32 vcc, s16, v16
	s_nop 1
	v_cndmask_b32_e32 v16, v16, v17, vcc
	v_rsq_f32_e32 v16, v16
	s_nop 0
	v_mul_f32_e32 v17, 0x45800000, v16
	v_cndmask_b32_e32 v16, v16, v17, vcc
	ds_write_b32 v0, v16 offset:4096
	s_cmp_gt_u32 s21, 3
	s_cbranch_scc0 .Letab_done
	v_ffbh_u32_e32 v26, v19
	v_min_u32_e32 v26, 32, v26
	v_lshlrev_b64 v[18:19], v26, v[18:19]
	v_min_u32_e32 v18, 1, v18
	v_or_b32_e32 v18, v19, v18
	v_cvt_f32_u32_e32 v18, v18
	v_sub_u32_e32 v19, 32, v26
	v_ldexp_f32 v18, v18, v19
	v_mul_f32_e32 v18, 0x31800000, v18
	v_fmamk_f32 v18, v18, 0x3a800000, v172
	v_mul_f32_e32 v19, 0x4b800000, v18
	v_cmp_gt_f32_e32 vcc, s16, v18
	s_nop 1
	v_cndmask_b32_e32 v18, v18, v19, vcc
	v_rsq_f32_e32 v18, v18
	s_nop 0
	v_mul_f32_e32 v19, 0x45800000, v18
	v_cndmask_b32_e32 v18, v18, v19, vcc
	ds_write_b32 v0, v18 offset:6144
	s_cmp_gt_u32 s21, 4
	s_cbranch_scc0 .Letab_done
	v_ffbh_u32_e32 v26, v21
	v_min_u32_e32 v26, 32, v26
	v_lshlrev_b64 v[20:21], v26, v[20:21]
	v_min_u32_e32 v20, 1, v20
	v_or_b32_e32 v20, v21, v20
	v_cvt_f32_u32_e32 v20, v20
	v_sub_u32_e32 v21, 32, v26
	v_ldexp_f32 v20, v20, v21
	v_mul_f32_e32 v20, 0x31800000, v20
	v_fmamk_f32 v20, v20, 0x3a800000, v172
	v_mul_f32_e32 v21, 0x4b800000, v20
	v_cmp_gt_f32_e32 vcc, s16, v20
	s_nop 1
	v_cndmask_b32_e32 v20, v20, v21, vcc
	v_rsq_f32_e32 v20, v20
	s_nop 0
	v_mul_f32_e32 v21, 0x45800000, v20
	v_cndmask_b32_e32 v20, v20, v21, vcc
	ds_write_b32 v0, v20 offset:8192
	s_cmp_gt_u32 s21, 5
	s_cbranch_scc0 .Letab_done
	v_ffbh_u32_e32 v26, v23
	v_min_u32_e32 v26, 32, v26
	v_lshlrev_b64 v[22:23], v26, v[22:23]
	v_min_u32_e32 v22, 1, v22
	v_or_b32_e32 v22, v23, v22
	v_cvt_f32_u32_e32 v22, v22
	v_sub_u32_e32 v23, 32, v26
	v_ldexp_f32 v22, v22, v23
	v_mul_f32_e32 v22, 0x31800000, v22
	v_fmamk_f32 v22, v22, 0x3a800000, v172
	v_mul_f32_e32 v23, 0x4b800000, v22
	v_cmp_gt_f32_e32 vcc, s16, v22
	s_nop 1
	v_cndmask_b32_e32 v22, v22, v23, vcc
	v_rsq_f32_e32 v22, v22
	s_nop 0
	v_mul_f32_e32 v23, 0x45800000, v22
	v_cndmask_b32_e32 v22, v22, v23, vcc
	ds_write_b32 v0, v22 offset:10240
.Letab_done:
.LBB0_478:
	s_or_b64 exec, exec, s[6:7]
	s_add_i32 s50, 0, 0x20000
	s_waitcnt lgkmcnt(0)
	s_barrier
